# selected-branch attention: loop-carried negated max and rescale threshold replace per-tile exec ladders; scalar tile offset for K/V prefetch addresses
# speedup vs baseline: 1.0110x; 1.0110x over previous
; template <int MODE>
; __device__ __forceinline__ void attn_branch(AttnState& st, const bf16_t* __restrict__ Kg, const bf16_t* __restrict__ Vg, u64 tiles, LAS bf16_t* KsB, LAS bf16_t* VtB,
;                                             int tq, u64 mymask, int cur, int fr, int fq, float (&imp)[16]) {
;     ...
;     if (tiles == 0ull) return;
;     int jb = __builtin_ctzll(tiles); tiles &= tiles - 1ull;
;     u32x4v kr = *(const u32x4v*)(Kg + (size_t)(jb * 64 + kkey) * 64 + kch * 8), vr = (u32x4v){0u, 0u, 0u, 0u};
; __device__ __forceinline__ void attn_phase(const Args& a, LAS unsigned char* lds) {
;     ...
;             u32x4v qvl[2][2];
; #pragma unroll
;             for (int ct = 0; ct < 2; ++ct)
; #pragma unroll
;                 for (int kk = 0; kk < 2; ++kk) { const int hq = g * 4 + 2 * ct + (fr >> 3); qvl[ct][kk] = *(const u32x4v*)(Q + row * 512 + hq * 64 + kk * 32 + fq * 8); }
;             float cs[8], sn[8];
; #pragma unroll
;             for (int e = 0; e < 8; ++e) { cs[e] = RT[(tq * 8 + e) * 2]; sn[e] = RT[(tq * 8 + e) * 2 + 1]; }
; #pragma unroll
;             for (int ct = 0; ct < 2; ++ct)
; #pragma unroll
;                 for (int kk = 0; kk < 2; ++kk) {
;                     const u32x4v qv = qvl[ct][kk];
;                     const unsigned qw[4] = {qv.x, qv.y, qv.z, qv.w};
;                     float r[8];
; #pragma unroll
;                     for (int e = 0; e < 8; ++e) {
;                         const float x = (e & 1) ? __uint_as_float(qw[e >> 1] & 0xffff0000u) : __uint_as_float(qw[e >> 1] << 16);
;                         if (kk == 0) { const float ot = __shfl_xor(x, 16); r[e] = (fq == 0 ? x * cs[e] - ot * sn[e] : (fq == 1 ? x * cs[e] + ot * sn[e] : x)) * ATT_QS; }
;                         else r[e] = x * ATT_QS;
;                     }
;                     u32x4v o; o.x = cvt_pk_bf16(r[0], r[1]); o.y = cvt_pk_bf16(r[2], r[3]); o.z = cvt_pk_bf16(r[4], r[5]); o.w = cvt_pk_bf16(r[6], r[7]);
;                     st.qf[ct][kk] = __builtin_bit_cast(bf16x8, o);
;                 }
;         }
; #pragma unroll
;         for (int ct = 0; ct < 2; ++ct) { st.m[ct] = -1e30f; st.l[ct] = 0.f;
; #pragma unroll
;             for (int dt = 0; dt < 4; ++dt) st.o[ct][dt] = (f32x4){0.f, 0.f, 0.f, 0.f}; }
;         attn_branch<M_SLC>(st, KV + 2 * KVSZ + (size_t)bg * 4096 * 64, KV + 3 * KVSZ + (size_t)bg * 4096 * 64, bun, Ks, Vt, tq, mymask, cur, fr, fq, imp);
.LBB0_1126:
	s_or_b64 exec, exec, s[16:17]
	s_waitcnt lgkmcnt(3)
	v_mul_f32_e32 v25, 0x3e38aa3b, v12
	v_mul_f32_e32 v12, 0x3e38aa3b, v42
	v_mul_f32_e32 v13, 0x3e38aa3b, v40
	v_mul_f32_e32 v4, 0x3e38aa3b, v36
	v_mul_f32_e32 v6, 0x3e38aa3b, v6
	v_mul_f32_e32 v7, 0x3e38aa3b, v44
	v_mul_f32_e32 v5, 0x3e38aa3b, v32
	v_mul_f32_e32 v14, 0x3e38aa3b, v38
	v_mul_f32_e32 v15, 0x3e38aa3b, v34
	v_cvt_pk_bf16_f32 v4, v6, v4
	v_cvt_pk_bf16_f32 v6, v13, v12
	v_lshlrev_b32_e32 v12, 16, v8
	v_and_b32_e32 v13, 0xffff0000, v8
	s_mov_b32 s16, 0x3e38aa3b
	v_lshlrev_b32_e32 v8, 16, v9
	v_and_b32_e32 v9, 0xffff0000, v9
	s_or_b64 s[2:3], s[4:5], s[2:3]
	v_cvt_pk_bf16_f32 v5, v14, v5
	v_cvt_pk_bf16_f32 v7, v7, v15
	v_pk_mul_f32 v[14:15], v[8:9], s[16:17] op_sel_hi:[1,0]
	v_lshlrev_b32_e32 v8, 16, v10
	v_and_b32_e32 v9, 0xffff0000, v10
	s_or_b64 s[2:3], s[2:3], s[6:7]
	v_mul_f32_e32 v0, 0x3e38aa3b, v22
	s_waitcnt lgkmcnt(0)
	v_mul_f32_e32 v3, 0x3e38aa3b, v20
	v_mul_f32_e32 v24, 0x3e38aa3b, v24
	v_pk_mul_f32 v[20:21], v[8:9], s[16:17] op_sel_hi:[1,0]
	v_lshlrev_b32_e32 v8, 16, v11
	v_and_b32_e32 v9, 0xffff0000, v11
	s_or_b64 s[2:3], s[2:3], s[8:9]
	v_mul_f32_e32 v2, 0x3e38aa3b, v2
	v_pk_mul_f32 v[22:23], v[8:9], s[16:17] op_sel_hi:[1,0]
	v_cvt_pk_bf16_f32 v9, v14, v15
	s_or_b64 s[2:3], s[2:3], s[10:11]
	v_cvt_pk_bf16_f32 v14, v24, v3
	v_cvt_pk_bf16_f32 v15, v0, v2
	v_lshlrev_b32_e32 v2, 16, v16
	v_and_b32_e32 v3, 0xffff0000, v16
	v_lshlrev_b32_e32 v16, 16, v17
	v_and_b32_e32 v17, 0xffff0000, v17
	v_cvt_pk_bf16_f32 v10, v20, v21
	s_or_b64 s[2:3], s[2:3], s[12:13]
	v_pk_mul_f32 v[20:21], v[16:17], s[16:17] op_sel_hi:[1,0]
	v_lshlrev_b32_e32 v16, 16, v18
	v_and_b32_e32 v17, 0xffff0000, v18
	v_mul_f32_e32 v26, 0x3e38aa3b, v30
	v_pk_mul_f32 v[12:13], v[12:13], s[16:17] op_sel_hi:[1,0]
	v_cvt_pk_bf16_f32 v11, v22, v23
	s_or_b64 s[2:3], s[2:3], s[14:15]
	v_pk_mul_f32 v[22:23], v[16:17], s[16:17] op_sel_hi:[1,0]
	v_lshlrev_b32_e32 v16, 16, v19
	v_and_b32_e32 v17, 0xffff0000, v19
	v_mul_f32_e32 v27, 0x3e38aa3b, v28
	v_mul_f32_e32 v28, 0x3e38aa3b, v46
	v_cvt_pk_bf16_f32 v8, v12, v13
	v_cvt_pk_bf16_f32 v13, v26, v25
	v_pk_mul_f32 v[2:3], v[2:3], s[16:17] op_sel_hi:[1,0]
	v_pk_mul_f32 v[24:25], v[16:17], s[16:17] op_sel_hi:[1,0]
	s_or_b64 s[0:1], s[2:3], s[0:1]
	s_lshl_b32 s14, s40, 18
	v_cvt_pk_bf16_f32 v12, v28, v27
	v_cvt_pk_bf16_f32 v16, v2, v3
	v_cvt_pk_bf16_f32 v17, v20, v21
	v_cvt_pk_bf16_f32 v18, v22, v23
	v_cvt_pk_bf16_f32 v19, v24, v25
	v_mov_b32_e32 v0, v199
	s_cmp_eq_u64 s[0:1], 0
	s_cbranch_scc1 .LBB0_1161
	s_lshl_b32 s4, s14, 1
	v_readlane_b32 s2, v252, 23
	s_add_u32 s2, s2, s4
	v_readlane_b32 s3, v252, 24
	s_addc_u32 s3, s3, 0
	v_readlane_b32 s5, v252, 25
	s_add_u32 s6, s5, s4
	v_readlane_b32 s4, v252, 26
	v_ashrrev_i32_e32 v187, 3, v0
	s_addc_u32 s7, s4, 0
	s_ff1_i32_b64 s4, s[0:1]
	v_lshl_add_u32 v2, s4, 6, v187
	v_ashrrev_i32_e32 v3, 31, v2
	v_lshlrev_b32_e32 v0, 3, v0
	v_lshlrev_b64 v[2:3], 7, v[2:3]
	v_and_b32_e32 v0, 56, v0
	v_lshl_add_u64 v[20:21], s[6:7], 0, v[2:3]
	v_lshlrev_b32_e32 v0, 1, v0
	v_lshl_add_u64 v[20:21], v[20:21], 0, v[0:1]
	v_lshl_add_u64 v[2:3], s[2:3], 0, v[2:3]
	v_lshl_add_u64 v[2:3], v[2:3], 0, v[0:1]
	global_load_dwordx4 v[36:39], v[20:21], off
	global_load_dwordx4 v[40:43], v[2:3], off
	v_or_b32_e32 v21, s39, v126
	v_or_b32_e32 v22, 2, v21
	v_cmp_le_i32_e64 s[42:43], v22, v152
	v_or_b32_e32 v22, 3, v21
	v_cmp_le_i32_e64 s[44:45], v22, v152
	v_or_b32_e32 v22, 16, v21
	v_cmp_le_i32_e64 s[46:47], v22, v152
	v_or_b32_e32 v22, 17, v21
	v_cmp_le_i32_e64 s[48:49], v22, v152
	v_or_b32_e32 v22, 18, v21
	v_cmp_le_i32_e64 s[50:51], v22, v152
	v_or_b32_e32 v22, 19, v21
	v_cmp_le_i32_e64 s[52:53], v22, v152
	v_or_b32_e32 v22, 32, v21
	v_cmp_le_i32_e64 s[54:55], v22, v152
	v_or_b32_e32 v22, 33, v21
	v_cmp_le_i32_e64 s[56:57], v22, v152
	v_or_b32_e32 v22, 34, v21
	v_cmp_le_i32_e64 s[58:59], v22, v152
	v_or_b32_e32 v22, 35, v21
	v_cmp_le_i32_e64 s[60:61], v22, v152
	v_or_b32_e32 v22, 48, v21
	s_movk_i32 s5, 0x48
	v_cmp_le_i32_e64 s[62:63], v22, v152
	v_or_b32_e32 v22, 49, v21
	s_add_u32 s8, s0, -1
	v_mul_lo_u32 v20, v187, s5
	v_cmp_le_i32_e64 s[64:65], v22, v152
	v_or_b32_e32 v22, 50, v21
	v_or_b32_e32 v21, 51, v21
	v_mov_b32_e32 v44, v1
	v_mov_b32_e32 v45, v1
	v_mov_b32_e32 v46, v1
	v_mov_b32_e32 v47, v1
	s_addc_u32 s9, s1, -1
	v_cmp_le_i32_e64 s[66:67], v22, v152
	v_cmp_le_i32_e64 s[68:69], v21, v152
	v_mov_b32_e32 v158, 0
	v_lshlrev_b32_e32 v189, 1, v20
	v_mov_b64_e32 v[50:51], v[46:47]
	v_mov_b64_e32 v[54:55], v[46:47]
	v_mov_b64_e32 v[58:59], v[46:47]
	v_mov_b64_e32 v[28:29], v[44:45]
	v_mov_b64_e32 v[32:33], v[44:45]
	v_mov_b64_e32 v[24:25], v[44:45]
	v_mov_b64_e32 v[20:21], v[44:45]
	s_and_b64 s[0:1], s[8:9], s[0:1]
	v_lshl_add_u64 v[2:3], s[6:7], 0, v[0:1]
	v_lshl_add_u64 v[160:161], s[2:3], 0, v[0:1]
	v_lshlrev_b32_e32 v60, 7, v187
	v_mov_b32_e32 v61, 0
	v_lshl_add_u64 v[2:3], v[2:3], 0, v[60:61]
	v_lshl_add_u64 v[160:161], v[160:161], 0, v[60:61]
	s_mov_b32 s15, 0
	v_mov_b32_e32 v190, 0xf149f2ca
	v_mov_b32_e32 v188, 0
	v_mov_b32_e32 v193, 0
	v_mov_b32_e32 v191, 0xf149f2ca
	v_mov_b32_e32 v192, 0
	v_mov_b32_e32 v200, 0
	v_mov_b32_e32 v201, 0xefa18f08
	v_mov_b32_e32 v202, 0xefa18f08
	v_mov_b64_e32 v[48:49], v[44:45]
	v_mov_b64_e32 v[52:53], v[44:45]
	v_mov_b64_e32 v[56:57], v[44:45]
	v_mov_b64_e32 v[30:31], v[46:47]
	v_mov_b64_e32 v[34:35], v[46:47]
	v_mov_b64_e32 v[26:27], v[46:47]
	v_mov_b64_e32 v[22:23], v[46:47]
	v_mov_b32_e32 v159, v158
.LBB0_1128:
	s_mul_i32 s2, s15, 0x2400
	s_add_i32 s17, s2, 0
	v_add3_u32 v60, v193, v189, v0
	s_waitcnt vmcnt(1)
	ds_write_b128 v60, v[36:39]
	v_add3_u32 v60, s17, v189, v0
	s_cmp_eq_u64 s[0:1], 0
	s_mov_b64 s[2:3], 0
	s_waitcnt vmcnt(0)
	ds_write_b128 v60, v[40:43] offset:18432
	s_cbranch_scc1 .LBB0_1130
	s_ff1_i32_b64 s16, s[0:1]
	s_lshl_b32 s8, s16, 13
	s_mov_b32 s9, 0
	v_lshl_add_u64 v[38:39], s[8:9], 0, v[2:3]
	v_lshl_add_u64 v[40:41], s[8:9], 0, v[160:161]
	global_load_dwordx4 v[36:39], v[38:39], off
	s_nop 0
	global_load_dwordx4 v[40:43], v[40:41], off
	s_add_u32 s2, s0, -1
	s_addc_u32 s3, s1, -1
	s_and_b64 s[2:3], s[2:3], s[0:1]
	s_branch .LBB0_1131

; #define LAS __attribute__((address_space(3)))
; template <int MODE, bool FAST, bool DEFER>
; __device__ __forceinline__ void attn_tile(AttnState& st, const LAS bf16_t* Ks, const LAS bf16_t* Vt, int jb, int tq, bool mybit, int fr, int fq, float (&imp)[16], float& prev_t3, bf16x8 (&pfo)[2][2]) {
;     ...
;     for (int ct = 0; ct < 2; ++ct) { const float nb_ = !FAST ? 0.f : ((MODE == M_SLC && !mybit) ? -1e30f : (st.m[ct] < -1e29f ? 0.f : -st.m[ct])); zinit[ct] = (f32x4){nb_, nb_, nb_, nb_}; }
; #pragma unroll
;     for (int sb = 0; sb < 4; ++sb) {
;         const bf16x8 k0 = *(const LAS bf16x8*)(Ks + (sb * 16 + fr) * KSTR + fq * 8);
;         const bf16x8 k1 = *(const LAS bf16x8*)(Ks + (sb * 16 + fr) * KSTR + 32 + fq * 8);
; #pragma unroll
;         for (int ct = 0; ct < 2; ++ct) {
;             f32x4 z = zinit[ct];
;             z = __builtin_amdgcn_mfma_f32_16x16x32_bf16(k0, st.qf[ct][0], z, 0, 0, 0);
;             z = __builtin_amdgcn_mfma_f32_16x16x32_bf16(k1, st.qf[ct][1], z, 0, 0, 0);
;             s[ct][sb] = ISCMP ? z * ATT_QS : z;
;         }
;     }
;     ...
;     if (FAST) {
;         float tz[2]; bool nd[2]; bool un[2];
; #pragma unroll
;         for (int ct = 0; ct < 2; ++ct) {
;             float t = -1e30f;
; #pragma unroll
;             for (int sb = 0; sb < 4; ++sb)
; #pragma unroll
;                 for (int j = 0; j < 4; ++j) t = fmaxf(t, s[ct][sb][j]);
;             t = fmaxf(t, __shfl_xor(t, 16)); t = fmaxf(t, __shfl_xor(t, 32));
;             tz[ct] = t; un[ct] = st.m[ct] < -1e29f;
;             nd[ct] = (t > -1e29f) && (t > ATT_THR || un[ct]);
;         }
;         if (__builtin_amdgcn_ballot_w64(nd[0] || nd[1]) != 0ull) {
; #pragma unroll
;             for (int ct = 0; ct < 2; ++ct) {
;                 const float dl = nd[ct] ? tz[ct] : 0.f;
;                 const float alpha = nd[ct] ? (un[ct] ? 0.f : __builtin_amdgcn_exp2f(-tz[ct])) : 1.f;
;                 st.m[ct] = nd[ct] ? ((un[ct] ? 0.f : st.m[ct]) + tz[ct]) : st.m[ct];
;                 st.l[ct] *= alpha;
; #pragma unroll
;                 for (int dt = 0; dt < 4; ++dt) st.o[ct][dt] = st.o[ct][dt] * alpha;
; #pragma unroll
;                 for (int sb = 0; sb < 4; ++sb) s[ct][sb] = s[ct][sb] - dl;
;             }
.LBB0_1131:
	v_lshrrev_b64 v[60:61], s4, v[156:157]
	v_and_b32_e32 v60, 1, v60
	v_cmp_ne_u32_e64 s[70:71], 0, v60
	s_and_b64 vcc, exec, s[70:71]
	s_waitcnt lgkmcnt(0)
	s_barrier
	s_cbranch_vccz .LBB0_1157
	s_cmp_eq_u32 s4, s37
	s_mov_b64 s[0:1], -1
	s_cbranch_scc1 .LBB0_1152
	v_cndmask_b32_e64 v64, v227, v192, s[70:71]
	v_cndmask_b32_e64 v60, v227, v200, s[70:71]
	v_add3_u32 v198, v193, v164, v183
	ds_read_b128 v[68:71], v198
	ds_read_b128 v[72:75], v198 offset:2304
	ds_read_b128 v[76:79], v198 offset:4608
	ds_read_b128 v[80:83], v198 offset:6912
	ds_read_b128 v[84:87], v198 offset:64
	ds_read_b128 v[88:91], v198 offset:2368
	ds_read_b128 v[194:197], v198 offset:4672
	ds_read_b128 v[206:209], v198 offset:6976
	v_mov_b32_e32 v65, v64
	v_mov_b32_e32 v61, v60
	v_mov_b64_e32 v[66:67], v[64:65]
	v_mov_b64_e32 v[62:63], v[60:61]
	s_waitcnt lgkmcnt(7)
	v_mfma_f32_16x16x32_bf16 v[108:111], v[68:71], v[4:7], v[64:67]
	v_mfma_f32_16x16x32_bf16 v[96:99], v[68:71], v[12:15], v[60:63]
	s_waitcnt lgkmcnt(6)
	v_mfma_f32_16x16x32_bf16 v[116:119], v[72:75], v[4:7], v[64:67]
	v_mfma_f32_16x16x32_bf16 v[100:103], v[72:75], v[12:15], v[60:63]
	s_waitcnt lgkmcnt(5)
	v_mfma_f32_16x16x32_bf16 v[112:115], v[76:79], v[4:7], v[64:67]
	v_mfma_f32_16x16x32_bf16 v[92:95], v[76:79], v[12:15], v[60:63]
	s_waitcnt lgkmcnt(4)
	v_mfma_f32_16x16x32_bf16 v[120:123], v[80:83], v[4:7], v[64:67]
	v_mfma_f32_16x16x32_bf16 v[104:107], v[80:83], v[12:15], v[60:63]
	s_waitcnt lgkmcnt(3)
	v_mfma_f32_16x16x32_bf16 v[108:111], v[84:87], v[8:11], v[108:111]
	v_mfma_f32_16x16x32_bf16 v[96:99], v[84:87], v[16:19], v[96:99]
	s_waitcnt lgkmcnt(2)
	v_mfma_f32_16x16x32_bf16 v[116:119], v[88:91], v[8:11], v[116:119]
	v_mfma_f32_16x16x32_bf16 v[100:103], v[88:91], v[16:19], v[100:103]
	s_waitcnt lgkmcnt(1)
	v_mfma_f32_16x16x32_bf16 v[112:115], v[194:197], v[8:11], v[112:115]
	v_mfma_f32_16x16x32_bf16 v[92:95], v[194:197], v[16:19], v[92:95]
	s_waitcnt lgkmcnt(0)
	v_mfma_f32_16x16x32_bf16 v[120:123], v[206:209], v[8:11], v[120:123]
	v_mfma_f32_16x16x32_bf16 v[104:107], v[206:209], v[16:19], v[104:107]
	s_nop 3
	v_max3_f32 v60, v108, s36, v109
	v_max3_f32 v60, v60, v110, v111
	v_max3_f32 v60, v60, v116, v117
	v_max3_f32 v60, v60, v118, v119
	v_max3_f32 v60, v60, v112, v113
	v_max3_f32 v60, v60, v114, v115
	v_max3_f32 v60, v60, v120, v121
	v_max3_f32 v60, v60, v122, v123
	ds_bpermute_b32 v61, v185, v60
	s_waitcnt lgkmcnt(0)
	v_max_f32_e32 v60, v60, v61
	ds_bpermute_b32 v61, v153, v60
	s_waitcnt lgkmcnt(0)
	v_max_f32_e32 v203, v60, v61
	v_cmp_gt_f32_e64 s[8:9], v203, v201
.LBB0_1145:
	v_max3_f32 v60, v96, s36, v97
	v_max3_f32 v60, v60, v98, v99
	v_max3_f32 v60, v60, v100, v101
	v_max3_f32 v60, v60, v102, v103
	v_max3_f32 v60, v60, v92, v93
	v_max3_f32 v60, v60, v94, v95
	v_max3_f32 v60, v60, v104, v105
	v_max3_f32 v60, v60, v106, v107
	ds_bpermute_b32 v61, v185, v60
	s_waitcnt lgkmcnt(0)
	v_max_f32_e32 v60, v60, v61
	ds_bpermute_b32 v61, v153, v60
	s_waitcnt lgkmcnt(0)
	v_max_f32_e32 v204, v60, v61
	v_cmp_gt_f32_e64 s[6:7], v204, v202
.LBB0_1149:
	v_add3_u32 v248, s17, v167, v184
	ds_read_b64_tr_b16 v[68:69], v248 offset:18432
	ds_read_b64_tr_b16 v[70:71], v248 offset:20736
	ds_read_b64_tr_b16 v[72:73], v248 offset:18464
	ds_read_b64_tr_b16 v[74:75], v248 offset:20768
	ds_read_b64_tr_b16 v[76:77], v248 offset:18496
	ds_read_b64_tr_b16 v[78:79], v248 offset:20800
	ds_read_b64_tr_b16 v[80:81], v248 offset:18528
	ds_read_b64_tr_b16 v[82:83], v248 offset:20832
	ds_read_b64_tr_b16 v[210:211], v248 offset:23040
	ds_read_b64_tr_b16 v[212:213], v248 offset:25344
	ds_read_b64_tr_b16 v[230:231], v248 offset:23072
	ds_read_b64_tr_b16 v[232:233], v248 offset:25376
	ds_read_b64_tr_b16 v[234:235], v248 offset:23104
	ds_read_b64_tr_b16 v[236:237], v248 offset:25408
	ds_read_b64_tr_b16 v[238:239], v248 offset:23136
	ds_read_b64_tr_b16 v[240:241], v248 offset:25440
	s_or_b64 s[10:11], s[8:9], s[6:7]
	s_and_b64 vcc, exec, s[10:11]
	s_cbranch_vccz .LBB0_1151
	v_cmp_gt_f32_e64 s[0:1], 0, v201
	v_cmp_gt_f32_e64 s[4:5], 0, v202
	v_exp_f32_e64 v60, -v203
	v_exp_f32_e64 v215, -v204
	v_cndmask_b32_e64 v214, 0, v203, s[8:9]
	v_cndmask_b32_e64 v61, v190, 0, s[0:1]
	v_cndmask_b32_e64 v60, v60, 0, s[0:1]
	v_sub_f32_e32 v108, v108, v214
	v_sub_f32_e32 v109, v109, v214
	v_sub_f32_e32 v110, v110, v214
	v_sub_f32_e32 v111, v111, v214
	v_sub_f32_e32 v116, v116, v214
	v_sub_f32_e32 v117, v117, v214
	v_sub_f32_e32 v118, v118, v214
	v_sub_f32_e32 v119, v119, v214
	v_sub_f32_e32 v112, v112, v214
	v_sub_f32_e32 v113, v113, v214
	v_sub_f32_e32 v114, v114, v214
	v_sub_f32_e32 v115, v115, v214
	v_sub_f32_e32 v120, v120, v214
	v_sub_f32_e32 v121, v121, v214
	v_sub_f32_e32 v122, v122, v214
	v_sub_f32_e32 v123, v123, v214
	v_cndmask_b32_e64 v214, v215, 0, s[4:5]
	v_cndmask_b32_e64 v215, v191, 0, s[4:5]
	v_add_f32_e32 v61, v61, v203
	v_cndmask_b32_e64 v60, 1.0, v60, s[8:9]
	v_cndmask_b32_e64 v129, 0, v204, s[6:7]
	v_cndmask_b32_e64 v214, 1.0, v214, s[6:7]
	v_add_f32_e32 v215, v215, v204
	v_cndmask_b32_e64 v190, v190, v61, s[8:9]
	v_mul_f32_e32 v159, v159, v60
	v_pk_mul_f32 v[46:47], v[46:47], v[60:61] op_sel_hi:[1,0]
	v_pk_mul_f32 v[44:45], v[44:45], v[60:61] op_sel_hi:[1,0]
	v_pk_mul_f32 v[50:51], v[50:51], v[60:61] op_sel_hi:[1,0]
	v_pk_mul_f32 v[48:49], v[48:49], v[60:61] op_sel_hi:[1,0]
	v_pk_mul_f32 v[54:55], v[54:55], v[60:61] op_sel_hi:[1,0]
	v_pk_mul_f32 v[52:53], v[52:53], v[60:61] op_sel_hi:[1,0]
	v_pk_mul_f32 v[58:59], v[58:59], v[60:61] op_sel_hi:[1,0]
	v_pk_mul_f32 v[56:57], v[56:57], v[60:61] op_sel_hi:[1,0]
	v_cndmask_b32_e64 v191, v191, v215, s[6:7]
	v_mul_f32_e32 v158, v158, v214
	v_pk_mul_f32 v[30:31], v[30:31], v[214:215] op_sel_hi:[1,0]
	v_pk_mul_f32 v[28:29], v[28:29], v[214:215] op_sel_hi:[1,0]
	v_pk_mul_f32 v[34:35], v[34:35], v[214:215] op_sel_hi:[1,0]
	v_pk_mul_f32 v[32:33], v[32:33], v[214:215] op_sel_hi:[1,0]
	v_pk_mul_f32 v[26:27], v[26:27], v[214:215] op_sel_hi:[1,0]
	v_pk_mul_f32 v[24:25], v[24:25], v[214:215] op_sel_hi:[1,0]
	v_pk_mul_f32 v[22:23], v[22:23], v[214:215] op_sel_hi:[1,0]
	v_pk_mul_f32 v[20:21], v[20:21], v[214:215] op_sel_hi:[1,0]
	v_sub_f32_e32 v96, v96, v129
	v_sub_f32_e32 v97, v97, v129
	v_sub_f32_e32 v98, v98, v129
	v_sub_f32_e32 v99, v99, v129
	v_sub_f32_e32 v100, v100, v129
	v_sub_f32_e32 v101, v101, v129
	v_sub_f32_e32 v102, v102, v129
	v_sub_f32_e32 v103, v103, v129
	v_sub_f32_e32 v92, v92, v129
	v_sub_f32_e32 v93, v93, v129
	v_sub_f32_e32 v94, v94, v129
	v_sub_f32_e32 v95, v95, v129
	v_sub_f32_e32 v104, v104, v129
	v_sub_f32_e32 v105, v105, v129
	v_sub_f32_e32 v106, v106, v129
	v_sub_f32_e32 v107, v107, v129
	v_cndmask_b32_e64 v192, v192, -v190, s[8:9]
	v_cndmask_b32_e64 v200, v200, -v191, s[6:7]
	v_mov_b32_e32 v129, 0x40c00000
	v_cndmask_b32_e64 v201, v201, v129, s[8:9]
	v_cndmask_b32_e64 v202, v202, v129, s[6:7]
